# asym P0: w_in tiles 1/2/2/3 per batch, later-GEMM tiles 0/1/4/6 per batch
# baseline (speedup 1.0000x reference)
.LBB0_34:
	s_cmp_lg_u32 s100, 0
	s_cbranch_scc1 .Lp0_go
	s_lshr_b32 s0, s83, 6
	s_and_b32 s1, s83, 63
	s_movk_i32 s4, 1
	s_movk_i32 s5, 0
	s_cmp_eq_u32 s0, 1
	s_cselect_b32 s4, 2, s4
	s_cselect_b32 s5, 64, s5
	s_cmp_eq_u32 s0, 2
	s_cselect_b32 s4, 2, s4
	s_cselect_b32 s5, 192, s5
	s_cmp_eq_u32 s0, 3
	s_cselect_b32 s4, 3, s4
	s_cselect_b32 s5, 320, s5
	s_mul_i32 s6, s1, s4
	s_add_i32 s8, s5, s6
	s_add_i32 s10, s8, s4

.LBB0_155:
	s_or_b64 exec, exec, s[0:1]
	s_mov_b32 s100, 1
	s_lshr_b32 s0, s83, 6
	s_and_b32 s1, s83, 63
	s_movk_i32 s4, 0
	s_movk_i32 s5, 512
	s_cmp_eq_u32 s0, 1
	s_cselect_b32 s4, 1, s4
	s_cselect_b32 s5, 512, s5
	s_cmp_eq_u32 s0, 2
	s_cselect_b32 s4, 4, s4
	s_cselect_b32 s5, 576, s5
	s_cmp_eq_u32 s0, 3
	s_cselect_b32 s4, 6, s4
	s_cselect_b32 s5, 832, s5
	s_mul_i32 s6, s1, s4
	s_add_i32 s8, s5, s6
	s_add_i32 s10, s8, s4
	s_cmp_eq_u32 s4, 0
	s_cbranch_scc1 .Lp0_second_done
	s_mul_i32 s3, s62, 0x2080
	s_mov_b32 s33, s3
	s_branch .LBB0_34
